# merge-first by bit 8 plus mixers item order reversed (attention first, LRU last) for blocks with bit 8 set
# baseline (speedup 1.0000x reference)
.LBB0_260:
	s_or_b64 exec, exec, s[8:9]
	v_readlane_b32 s0, v236, 55
	v_readlane_b32 s1, v236, 56
	s_and_b64 vcc, exec, s[0:1]
	s_waitcnt lgkmcnt(0)
	s_barrier
	s_cbranch_vccz .LBB0_120
	v_readlane_b32 s0, v236, 3
	v_readlane_b32 s1, v236, 4
	s_andn2_b64 vcc, exec, s[0:1]
	s_cbranch_vccnz .LBB0_329
	v_readlane_b32 s0, v236, 57
	s_lshl_b32 s30, s0, 1
	v_readlane_b32 s0, v236, 36
	s_mov_b32 s31, s0
	s_bfe_u32 s1, s0, 0x10008
	s_cmpk_lg_i32 s2, 0x200
	s_cselect_b32 s1, 0, s1
	s_lshl_b32 s1, s1, 10
	s_add_i32 s31, s31, s1
	v_readlane_b32 s1, v236, 37
	s_branch .LBB0_265

.LBB0_264:
	s_bfe_u32 s0, s31, 0x10008
	s_cmpk_lg_i32 s2, 0x200
	s_cselect_b32 s0, 0, s0
	s_cmp_eq_u32 s0, 0
	s_cbranch_scc1 .Lmix_fwd
	s_sub_i32 s31, s31, s2
	s_cmp_lt_i32 s31, 0
	s_cbranch_scc1 .LBB0_329
	s_branch .LBB0_265
